# attention loop top: steady-state path waits only for K-image loads (vmcnt 24), epilogue stores stay in flight; first-iteration copy keeps original counts
# speedup vs baseline: 1.0028x; 1.0028x over previous
.LBB0_713:
	v_add_u32_e32 v22, s93, v107
	v_add_u32_e32 v23, 0xa000, v47
	v_add_u32_e32 v30, 0xc000, v47
	v_add_u32_e32 v31, 0xe000, v47
	v_add_u32_e32 v38, 0x10000, v47
	v_add_u32_e32 v39, 0x12000, v47
	v_add_u32_e32 v48, 0x14000, v47
	v_add_u32_e32 v47, 0x16000, v47
	v_lshl_add_u32 v22, v22, s83, v46
	v_lshl_add_u32 v26, v23, s83, v46
	v_lshl_add_u32 v30, v30, s83, v46
	v_lshl_add_u32 v34, v31, s83, v46
	v_lshl_add_u32 v38, v38, s83, v46
	v_lshl_add_u32 v42, v39, s83, v46
	v_lshl_add_u32 v48, v48, s83, v46
	s_waitcnt vmcnt(16)
	v_lshl_add_u32 v50, v47, s83, v46
	global_load_dwordx4 v[22:25], v22, s[70:71]
	s_nop 0
	global_load_dwordx4 v[26:29], v26, s[70:71]
	s_nop 0
	global_load_dwordx4 v[30:33], v30, s[70:71]
	s_nop 0
	global_load_dwordx4 v[34:37], v34, s[70:71]
	s_nop 0
	global_load_dwordx4 v[38:41], v38, s[70:71]
	s_nop 0
	global_load_dwordx4 v[42:45], v42, s[70:71]
	s_nop 0
	global_load_dwordx4 v[46:49], v48, s[70:71]
	s_nop 0
	global_load_dwordx4 v[50:53], v50, s[70:71]
	v_and_b32_e32 v55, 15, v54
	v_lshrrev_b32_e32 v2, 4, v54
	s_ashr_i32 s0, s8, 8
	s_bfe_u32 s1, s8, 0x20006
	v_bfe_u32 v56, v54, 4, 2
	s_lshl_b32 s8, s0, 3
	s_lshl_b32 s9, s1, 1
	v_bitop3_b32 v2, v2, v55, 3 bitop3:0x6c
	s_or_b32 s10, s9, s8
	v_lshlrev_b32_e32 v58, 4, v2
	v_bitop3_b32 v2, v56, v55, 4 bitop3:0x36
	s_lshl_b32 s8, s10, 12
	v_lshlrev_b32_e32 v59, 4, v2
	v_bitop3_b32 v2, v56, v55, 8 bitop3:0x36
	v_lshlrev_b32_e32 v62, 3, v54
	s_add_i32 s8, s8, 0
	v_lshlrev_b32_e32 v60, 4, v2
	v_bitop3_b32 v2, v56, v55, 12 bitop3:0x36
	v_and_b32_e32 v63, 16, v62
	v_lshlrev_b32_e32 v4, 2, v56
	v_lshl_add_u32 v57, v55, 8, s8
	v_lshlrev_b32_e32 v61, 4, v2
	v_bfe_u32 v2, v54, 2, 2
	s_lshl_b32 s8, s10, 4
	v_add_u32_e32 v63, 0, v63
	v_and_or_b32 v5, v4, 4, v2
	v_or3_b32 v2, s8, v4, v2
	v_and_or_b32 v62, v62, 8, v63
	v_lshl_add_u32 v2, v2, 8, v62
	v_lshlrev_b32_e32 v5, 5, v5
	s_movk_i32 s8, 0x60
	v_xad_u32 v112, v5, s8, v2
	s_movk_i32 s8, 0x80
	v_xad_u32 v113, v5, s8, v2
	s_movk_i32 s8, 0xa0
	v_xad_u32 v114, v5, s8, v2
	s_movk_i32 s8, 0xc0
	s_lshl_b32 s20, s0, 7
	s_lshl_b32 s1, s1, 5
	v_xad_u32 v115, v5, s8, v2
	s_movk_i32 s8, 0xe0
	s_cmp_gt_i32 s10, 7
	v_xad_u32 v116, v5, s8, v2
	s_cselect_b64 s[8:9], -1, 0
	s_cmp_gt_i32 s10, 6
	s_cselect_b64 s[12:13], -1, 0
	s_cmp_gt_i32 s10, 5
	s_cselect_b64 s[14:15], -1, 0
	s_cmp_gt_i32 s10, 4
	s_cselect_b64 s[26:27], -1, 0
	s_cmp_gt_i32 s10, 3
	s_cselect_b64 s[34:35], -1, 0
	s_cmp_gt_i32 s10, 2
	s_cselect_b64 s[36:37], -1, 0
	s_cmp_gt_i32 s10, 1
	s_cselect_b64 s[56:57], -1, 0
	s_cmp_gt_i32 s10, 0
	v_add_u32_e32 v109, v2, v5
	v_xad_u32 v110, v5, 32, v2
	v_xad_u32 v111, v5, 64, v2
	v_ashrrev_i32_e32 v2, 4, v54
	s_cselect_b64 s[62:63], -1, 0
	s_cmp_gt_i32 s0, -1
	v_xor_b32_e32 v5, v2, v54
	s_cselect_b64 s[66:67], -1, 0
	s_cmp_gt_i32 s10, -2
	v_sub_u32_e32 v62, v4, v55
	v_lshl_add_u32 v4, v2, 8, 0
	v_lshlrev_b32_e32 v5, 4, v5
	v_lshlrev_b32_e32 v2, 1, v2
	s_cselect_b64 s[10:11], -1, 0
	s_or_b32 s0, s20, s1
	v_and_b32_e32 v5, 0xf0, v5
	v_bitop3_b32 v2, v2, v55, 14 bitop3:0x6c
	v_or_b32_e32 v127, s0, v55
	v_readlane_b32 s0, v241, 47
	v_add_u32_e32 v117, v4, v5
	v_lshl_add_u32 v118, v2, 4, v4
	v_lshlrev_b32_e32 v2, 3, v56
	v_lshlrev_b32_e32 v4, 4, v56
	v_mov_b32_e32 v5, v3
	v_mov_b32_e32 v132, s0
	v_readlane_b32 s0, v241, 46
	v_lshl_add_u64 v[94:95], s[72:73], 0, v[4:5]
	v_lshl_add_u64 v[96:97], s[72:73], 0, v[2:3]
	v_cmp_eq_u32_e64 s[38:39], 0, v56
	v_add_u32_e32 v119, 0x10000, v117
	v_add_u32_e32 v120, 0x12000, v117
	v_add_u32_e32 v121, 0x14000, v117
	v_add_u32_e32 v122, 0x16000, v117
	v_cmp_lt_i32_e64 s[40:41], -1, v62
	v_cmp_lt_i32_e64 s[42:43], -2, v62
	v_cmp_lt_i32_e64 s[44:45], -3, v62
	v_cmp_lt_i32_e64 s[46:47], -4, v62
	v_cmp_gt_i32_e64 s[48:49], 1, v62
	v_cmp_gt_i32_e64 s[50:51], 0, v62
	v_cmp_gt_i32_e64 s[52:53], -1, v62
	v_cmp_gt_i32_e64 s[54:55], -2, v62
	v_add_u32_e32 v123, 0x10000, v118
	v_add_u32_e32 v124, 0x12000, v118
	v_add_u32_e32 v125, 0x14000, v118
	v_add_u32_e32 v126, 0x16000, v118
	v_add_u32_e32 v128, v57, v58
	v_add_u32_e32 v129, v57, v59
	v_add_u32_e32 v130, v57, v60
	v_add_u32_e32 v131, v57, v61
	v_readlane_b32 s79, v241, 49
	s_mov_b32 s30, s0
	v_readlane_b32 s20, v241, 45
	v_readlane_b32 s31, v241, 44
	v_readlane_b32 s78, v242, 10
	s_lshl_b32 s0, s31, 1
	v_lshl_add_u32 v2, s79, 8, v127
	s_lshl_b32 s24, s20, 4
	s_lshl_b32 s1, s31, 6
	s_add_i32 s24, s24, s30
	v_lshlrev_b32_e32 v54, s0, v2
	v_or_b32_e32 v2, 16, v2
	s_add_i32 s24, s24, s1
	v_lshlrev_b32_e32 v2, s0, v2
	s_ashr_i32 s25, s24, 31
	v_add_u32_e32 v102, v54, v132
	v_add_u32_e32 v98, v2, v132
	s_lshl_b64 s[24:25], s[24:25], 20
	v_ashrrev_i32_e32 v103, 31, v102
	v_ashrrev_i32_e32 v99, 31, v98
	v_lshl_add_u64 v[4:5], v[94:95], 0, s[24:25]
	v_lshlrev_b64 v[104:105], 8, v[102:103]
	v_lshlrev_b64 v[100:101], 8, v[98:99]
	v_lshl_add_u64 v[66:67], v[4:5], 0, v[104:105]
	v_lshl_add_u64 v[4:5], v[4:5], 0, v[100:101]
	global_load_dwordx4 v[54:57], v[66:67], off
	global_load_dwordx4 v[58:61], v[66:67], off offset:64
	global_load_dwordx4 v[62:65], v[66:67], off offset:128
	s_nop 0
	global_load_dwordx4 v[66:69], v[66:67], off offset:192
	s_nop 0
	global_load_dwordx4 v[70:73], v[4:5], off
	global_load_dwordx4 v[74:77], v[4:5], off offset:64
	global_load_dwordx4 v[78:81], v[4:5], off offset:128
	global_load_dwordx4 v[82:85], v[4:5], off offset:192
	s_lshl_b32 s1, s20, 24
	s_lshl_b32 s60, s30, 20
	s_waitcnt vmcnt(16)
	ds_write_b128 v117, v[6:9]
	ds_write_b128 v117, v[10:13] offset:8192
	ds_write_b128 v117, v[14:17] offset:16384
	ds_write_b128 v117, v[18:21] offset:24576
	s_waitcnt vmcnt(15)
	ds_write_b128 v117, v[22:25] offset:32768
	s_waitcnt vmcnt(14)
	ds_write_b128 v117, v[26:29] offset:40960
	s_waitcnt vmcnt(13)
	ds_write_b128 v117, v[30:33] offset:49152
	s_waitcnt vmcnt(12)
	ds_write_b128 v117, v[34:37] offset:57344
	s_waitcnt vmcnt(11)
	ds_write_b128 v119, v[38:41]
	s_waitcnt vmcnt(10)
	ds_write_b128 v120, v[42:45]
	s_waitcnt vmcnt(9)
	ds_write_b128 v121, v[46:49]
	s_waitcnt vmcnt(8)
	ds_write_b128 v122, v[50:53]
	s_branch .Lph0_join

.LBB0_715:
	s_lshl_b32 s0, s31, 1
	v_lshl_add_u32 v2, s79, 8, v127
	s_lshl_b32 s24, s20, 4
	s_lshl_b32 s1, s31, 6
	s_add_i32 s24, s24, s30
	v_lshlrev_b32_e32 v54, s0, v2
	v_or_b32_e32 v2, 16, v2
	s_add_i32 s24, s24, s1
	v_lshlrev_b32_e32 v2, s0, v2
	s_ashr_i32 s25, s24, 31
	v_add_u32_e32 v102, v54, v132
	v_add_u32_e32 v98, v2, v132
	s_lshl_b64 s[24:25], s[24:25], 20
	v_ashrrev_i32_e32 v103, 31, v102
	v_ashrrev_i32_e32 v99, 31, v98
	v_lshl_add_u64 v[4:5], v[94:95], 0, s[24:25]
	v_lshlrev_b64 v[104:105], 8, v[102:103]
	v_lshlrev_b64 v[100:101], 8, v[98:99]
	v_lshl_add_u64 v[66:67], v[4:5], 0, v[104:105]
	v_lshl_add_u64 v[4:5], v[4:5], 0, v[100:101]
	global_load_dwordx4 v[54:57], v[66:67], off
	global_load_dwordx4 v[58:61], v[66:67], off offset:64
	global_load_dwordx4 v[62:65], v[66:67], off offset:128
	s_nop 0
	global_load_dwordx4 v[66:69], v[66:67], off offset:192
	s_nop 0
	global_load_dwordx4 v[70:73], v[4:5], off
	global_load_dwordx4 v[74:77], v[4:5], off offset:64
	global_load_dwordx4 v[78:81], v[4:5], off offset:128
	global_load_dwordx4 v[82:85], v[4:5], off offset:192
	s_lshl_b32 s1, s20, 24
	s_lshl_b32 s60, s30, 20
	s_waitcnt vmcnt(24)
	ds_write_b128 v117, v[6:9]
	ds_write_b128 v117, v[10:13] offset:8192
	ds_write_b128 v117, v[14:17] offset:16384
	ds_write_b128 v117, v[18:21] offset:24576
	ds_write_b128 v117, v[22:25] offset:32768
	ds_write_b128 v117, v[26:29] offset:40960
	ds_write_b128 v117, v[30:33] offset:49152
	ds_write_b128 v117, v[34:37] offset:57344
	ds_write_b128 v119, v[38:41]
	ds_write_b128 v120, v[42:45]
	ds_write_b128 v121, v[46:49]
	ds_write_b128 v122, v[50:53]
.Lph0_join:
	v_lshl_or_b32 v2, v132, 8, v106
	s_add_i32 s1, s1, s60
	s_waitcnt lgkmcnt(0)
	s_barrier
	v_add_u32_e32 v50, s1, v2
	s_lshl_b32 s1, s79, 16
	s_cmp_gt_i32 s79, 0
	s_cselect_b64 s[76:77], -1, 0
	s_cmp_lt_i32 s79, 1
	v_add_u32_e32 v51, s1, v108
	s_cbranch_scc1 .LBB0_717
	v_lshl_add_u32 v2, v51, s0, v50
	v_add_u32_e32 v4, 0x2000, v51
	v_lshl_add_u32 v4, v4, s0, v50
	global_load_dwordx4 v[6:9], v2, s[18:19]
	global_load_dwordx4 v[10:13], v4, s[18:19]
	v_add_u32_e32 v2, 0x4000, v51
	v_lshl_add_u32 v2, v2, s0, v50
	v_add_u32_e32 v4, 0x6000, v51
	v_lshl_add_u32 v4, v4, s0, v50
	global_load_dwordx4 v[14:17], v2, s[18:19]
	global_load_dwordx4 v[18:21], v4, s[18:19]
	s_branch .LBB0_718

.LBB0_791:
	s_ashr_i32 s0, s8, 8
	s_bfe_u32 s1, s8, 0x20006
	v_and_b32_e32 v55, 15, v54
	v_lshrrev_b32_e32 v2, 4, v54
	s_lshl_b32 s8, s0, 3
	s_lshl_b32 s9, s1, 1
	v_bfe_u32 v4, v54, 4, 2
	s_or_b32 s8, s9, s8
	v_bitop3_b32 v2, v2, v55, 3 bitop3:0x6c
	s_lshl_b32 s9, s8, 12
	v_lshlrev_b32_e32 v58, 4, v2
	v_bitop3_b32 v2, v4, v55, 4 bitop3:0x36
	s_add_i32 s9, s9, 0
	v_lshlrev_b32_e32 v59, 4, v2
	v_bitop3_b32 v2, v4, v55, 8 bitop3:0x36
	v_lshl_add_u32 v57, v55, 8, s9
	v_lshlrev_b32_e32 v60, 4, v2
	v_bitop3_b32 v2, v4, v55, 12 bitop3:0x36
	v_readlane_b32 s9, v241, 57
	v_lshlrev_b32_e32 v61, 4, v2
	v_add_u32_e32 v5, 0xa000, v46
	v_add3_u32 v2, v179, s9, v38
	global_load_dwordx4 v[22:25], v2, s[70:71]
	global_load_dwordx4 v[26:29], v5, s[70:71]
	v_add_u32_e32 v2, 0xc000, v46
	s_mov_b32 s9, 0x10000
	v_add_u32_e32 v5, 0xe000, v46
	global_load_dwordx4 v[30:33], v2, s[70:71]
	global_load_dwordx4 v[34:37], v5, s[70:71]
	v_add3_u32 v2, v39, v38, s9
	v_add_u32_e32 v5, 0x12000, v46
	global_load_dwordx4 v[38:41], v2, s[70:71]
	global_load_dwordx4 v[42:45], v5, s[70:71]
	v_add_u32_e32 v2, 0x14000, v46
	v_add_u32_e32 v5, 0x16000, v46
	global_load_dwordx4 v[46:49], v2, s[70:71]
	global_load_dwordx4 v[50:53], v5, s[70:71]
	v_lshlrev_b32_e32 v62, 3, v54
	v_and_b32_e32 v63, 16, v62
	v_lshlrev_b32_e32 v56, 2, v4
	v_bfe_u32 v2, v54, 2, 2
	s_lshl_b32 s9, s8, 4
	v_add_u32_e32 v63, 0, v63
	v_and_or_b32 v5, v56, 4, v2
	v_or3_b32 v2, s9, v56, v2
	v_and_or_b32 v62, v62, 8, v63
	v_lshl_add_u32 v2, v2, 8, v62
	v_lshlrev_b32_e32 v5, 5, v5
	s_movk_i32 s9, 0x60
	v_xad_u32 v184, v5, s9, v2
	s_movk_i32 s9, 0x80
	v_xad_u32 v185, v5, s9, v2
	s_movk_i32 s9, 0xa0
	v_xad_u32 v186, v5, s9, v2
	s_movk_i32 s9, 0xc0
	v_xad_u32 v187, v5, s9, v2
	s_movk_i32 s9, 0xe0
	v_xad_u32 v188, v5, s9, v2
	s_lshl_b32 s9, s0, 7
	s_lshl_b32 s1, s1, 5
	s_cmp_gt_i32 s8, 7
	s_cselect_b64 s[86:87], -1, 0
	s_cmp_gt_i32 s8, 6
	s_cselect_b64 s[84:85], -1, 0
	s_cmp_gt_i32 s8, 5
	s_cselect_b64 s[82:83], -1, 0
	s_cmp_gt_i32 s8, 4
	s_cselect_b64 s[80:81], -1, 0
	s_cmp_gt_i32 s8, 3
	s_cselect_b64 s[78:79], -1, 0
	s_cmp_gt_i32 s8, 2
	s_cselect_b64 s[56:57], -1, 0
	s_cmp_gt_i32 s8, 1
	v_add_u32_e32 v181, v2, v5
	v_xad_u32 v182, v5, 32, v2
	v_xad_u32 v183, v5, 64, v2
	v_ashrrev_i32_e32 v2, 4, v54
	s_cselect_b64 s[66:67], -1, 0
	s_cmp_gt_i32 s8, 0
	v_xor_b32_e32 v54, v2, v54
	s_cselect_b64 s[14:15], -1, 0
	s_cmp_gt_i32 s0, -1
	v_lshl_add_u32 v5, v2, 8, 0
	v_lshlrev_b32_e32 v54, 4, v54
	v_lshlrev_b32_e32 v2, 1, v2
	s_cselect_b64 s[36:37], -1, 0
	s_cmp_gt_i32 s8, -2
	v_and_b32_e32 v54, 0xf0, v54
	v_bitop3_b32 v2, v2, v55, 14 bitop3:0x6c
	s_cselect_b64 s[12:13], -1, 0
	s_or_b32 s0, s9, s1
	v_sub_u32_e32 v62, v56, v55
	v_add_u32_e32 v189, v5, v54
	v_lshl_add_u32 v190, v2, 4, v5
	v_lshlrev_b32_e32 v2, 4, v4
	v_or_b32_e32 v205, s0, v55
	v_readlane_b32 s0, v241, 55
	v_lshl_add_u64 v[4:5], s[72:73], 0, v[2:3]
	v_add_u32_e32 v191, 0x10000, v189
	v_add_u32_e32 v192, 0x12000, v189
	v_add_u32_e32 v193, 0x14000, v189
	v_add_u32_e32 v194, 0x16000, v189
	v_cmp_lt_i32_e64 s[38:39], -1, v62
	v_cmp_lt_i32_e64 s[40:41], -2, v62
	v_cmp_lt_i32_e64 s[42:43], -3, v62
	v_cmp_lt_i32_e64 s[44:45], -4, v62
	v_cmp_gt_i32_e64 s[46:47], 1, v62
	v_cmp_gt_i32_e64 s[48:49], 0, v62
	v_cmp_gt_i32_e64 s[50:51], -1, v62
	v_cmp_gt_i32_e64 s[52:53], -2, v62
	v_add_u32_e32 v195, 0x10000, v190
	v_add_u32_e32 v196, 0x12000, v190
	v_add_u32_e32 v197, 0x14000, v190
	v_add_u32_e32 v204, 0x16000, v190
	v_add_u32_e32 v206, v57, v58
	v_add_u32_e32 v207, v57, v59
	v_add_u32_e32 v208, v57, v60
	v_add_u32_e32 v209, v57, v61
	v_lshlrev_b32_e32 v2, 1, v56
	v_readlane_b32 s94, v241, 58
	s_mov_b32 s20, s0
	v_readlane_b32 s97, v241, 54
	v_readlane_b32 s93, v242, 10
	s_lshl_b32 s0, s97, 4
	v_lshl_add_u32 v126, s94, 8, v205
	s_or_b32 s0, s0, s20
	s_ashr_i32 s1, s0, 31
	v_or_b32_e32 v122, 16, v126
	s_lshl_b64 s[10:11], s[0:1], 20
	v_ashrrev_i32_e32 v127, 31, v126
	v_ashrrev_i32_e32 v123, 31, v122
	v_lshl_add_u64 v[70:71], v[4:5], 0, s[10:11]
	v_lshlrev_b64 v[128:129], 8, v[126:127]
	v_lshlrev_b64 v[124:125], 8, v[122:123]
	v_lshl_add_u64 v[66:67], v[70:71], 0, v[128:129]
	v_lshl_add_u64 v[82:83], v[70:71], 0, v[124:125]
	global_load_dwordx4 v[54:57], v[66:67], off
	global_load_dwordx4 v[58:61], v[66:67], off offset:64
	global_load_dwordx4 v[62:65], v[66:67], off offset:128
	s_nop 0
	global_load_dwordx4 v[66:69], v[66:67], off offset:192
	s_nop 0
	global_load_dwordx4 v[70:73], v[82:83], off
	global_load_dwordx4 v[74:77], v[82:83], off offset:64
	global_load_dwordx4 v[78:81], v[82:83], off offset:128
	s_nop 0
	global_load_dwordx4 v[82:85], v[82:83], off offset:192
	s_waitcnt vmcnt(16)
	ds_write_b128 v189, v[6:9]
	ds_write_b128 v189, v[10:13] offset:8192
	ds_write_b128 v189, v[14:17] offset:16384
	ds_write_b128 v189, v[18:21] offset:24576
	s_waitcnt vmcnt(15)
	ds_write_b128 v189, v[22:25] offset:32768
	s_waitcnt vmcnt(14)
	ds_write_b128 v189, v[26:29] offset:40960
	s_waitcnt vmcnt(13)
	ds_write_b128 v189, v[30:33] offset:49152
	s_waitcnt vmcnt(12)
	ds_write_b128 v189, v[34:37] offset:57344
	s_waitcnt vmcnt(11)
	ds_write_b128 v191, v[38:41]
	s_waitcnt vmcnt(10)
	ds_write_b128 v192, v[42:45]
	s_waitcnt vmcnt(9)
	ds_write_b128 v193, v[46:49]
	s_waitcnt vmcnt(8)
	ds_write_b128 v194, v[50:53]
	s_branch .Lph1_join

.LBB0_795:
	s_lshl_b32 s0, s97, 4
	v_lshl_add_u32 v126, s94, 8, v205
	s_or_b32 s0, s0, s20
	s_ashr_i32 s1, s0, 31
	v_or_b32_e32 v122, 16, v126
	s_lshl_b64 s[10:11], s[0:1], 20
	v_ashrrev_i32_e32 v127, 31, v126
	v_ashrrev_i32_e32 v123, 31, v122
	v_lshl_add_u64 v[70:71], v[4:5], 0, s[10:11]
	v_lshlrev_b64 v[128:129], 8, v[126:127]
	v_lshlrev_b64 v[124:125], 8, v[122:123]
	v_lshl_add_u64 v[66:67], v[70:71], 0, v[128:129]
	v_lshl_add_u64 v[82:83], v[70:71], 0, v[124:125]
	global_load_dwordx4 v[54:57], v[66:67], off
	global_load_dwordx4 v[58:61], v[66:67], off offset:64
	global_load_dwordx4 v[62:65], v[66:67], off offset:128
	s_nop 0
	global_load_dwordx4 v[66:69], v[66:67], off offset:192
	s_nop 0
	global_load_dwordx4 v[70:73], v[82:83], off
	global_load_dwordx4 v[74:77], v[82:83], off offset:64
	global_load_dwordx4 v[78:81], v[82:83], off offset:128
	s_nop 0
	global_load_dwordx4 v[82:85], v[82:83], off offset:192
	s_waitcnt vmcnt(24)
	ds_write_b128 v189, v[6:9]
	ds_write_b128 v189, v[10:13] offset:8192
	ds_write_b128 v189, v[14:17] offset:16384
	ds_write_b128 v189, v[18:21] offset:24576
	ds_write_b128 v189, v[22:25] offset:32768
	ds_write_b128 v189, v[26:29] offset:40960
	ds_write_b128 v189, v[30:33] offset:49152
	ds_write_b128 v189, v[34:37] offset:57344
	ds_write_b128 v191, v[38:41]
	ds_write_b128 v192, v[42:45]
	ds_write_b128 v193, v[46:49]
	ds_write_b128 v194, v[50:53]
.Lph1_join:
	s_lshl_b32 s0, s97, 24
	s_lshl_b32 s1, s20, 20
	s_waitcnt lgkmcnt(0)
	s_barrier
	s_or_b32 s0, s0, s1
	s_lshl_b32 s62, s94, 16
	v_or_b32_e32 v38, s0, v178
	v_add_u32_e32 v39, s62, v180
	s_cmp_eq_u32 s94, 0
	v_add_u32_e32 v46, v38, v39
	s_cbranch_scc1 .LBB0_797
	s_movk_i32 s0, 0x4000
	v_add_u32_e32 v10, 0x2000, v46
	v_add3_u32 v14, v39, v38, s0
	v_add_u32_e32 v18, 0x6000, v46
	global_load_dwordx4 v[6:9], v46, s[18:19]
	s_nop 0
	global_load_dwordx4 v[10:13], v10, s[18:19]
	s_nop 0
	global_load_dwordx4 v[14:17], v14, s[18:19]
	s_nop 0
	global_load_dwordx4 v[18:21], v18, s[18:19]
	s_mov_b64 s[24:25], -1
	s_mov_b64 s[30:31], -1
	s_mov_b64 s[60:61], -1
	s_mov_b64 s[74:75], -1
	s_mov_b64 s[76:77], -1
	s_mov_b64 s[54:55], -1
	s_mov_b64 s[34:35], -1
	s_mov_b64 s[26:27], -1
	s_mov_b64 s[8:9], -1
	s_mov_b64 s[0:1], -1
	s_branch .LBB0_798
